# k15 with the GEMM2/GEMM3 code-touch ranges clamped to stay inside the kernel text
# baseline (speedup 1.0000x reference)
.LBB0_815:
	v_lshrrev_b32_e32 v16, 1, v14
	v_and_b32_e32 v15, 15, v14
	v_and_b32_e32 v163, 24, v16
	v_lshlrev_b32_e32 v14, 2, v14
	v_lshl_or_b32 v162, s15, 6, v15
	v_lshlrev_b32_e32 v16, 1, v163
	v_lshlrev_b32_e32 v15, 6, v15
	v_and_b32_e32 v14, 32, v14
	v_or_b32_e32 v17, v15, v16
	v_lshlrev_b32_e32 v132, 7, v162
	v_bitop3_b32 v15, v15, v14, v16 bitop3:0x36
	s_movk_i32 s9, 0xe000
	v_and_or_b32 v15, v132, s9, v15
	s_lshl_b32 s9, s16, 5
	s_mov_b64 s[16:17], 0x80
	s_and_b32 s18, s9, 0x60
	s_add_i32 m0, s19, 0x18000
	v_lshl_add_u64 v[6:7], v[6:7], 0, s[16:17]
	s_lshl_b32 s9, s18, 7
	s_waitcnt vmcnt(4)
	s_barrier
	global_load_lds_dwordx4 v[6:7], off
	v_lshl_add_u64 v[4:5], v[4:5], 0, s[16:17]
	s_add_i32 m0, s19, 0x1a000
	s_add_i32 s23, s19, 0x8000
	s_add_i32 s24, s19, 0xa000
	global_load_lds_dwordx4 v[4:5], off
	v_lshl_add_u64 v[2:3], v[2:3], 0, s[16:17]
	s_mov_b32 m0, s23
	s_add_u32 s0, s0, 0x40080
	global_load_lds_dwordx4 v[2:3], off
	v_lshl_add_u64 v[0:1], v[0:1], 0, s[16:17]
	s_mov_b32 m0, s24
	s_addc_u32 s1, s1, 0
	global_load_lds_dwordx4 v[0:1], off
	s_add_i32 m0, s19, 0x1c000
	v_lshl_add_u64 v[0:1], s[0:1], 0, v[150:151]
	global_load_lds_dwordx4 v[0:1], off
	v_lshl_add_u64 v[0:1], s[0:1], 0, v[154:155]
	s_add_i32 m0, s19, 0x1e000
	s_lshl_b32 s1, s5, 5
	global_load_lds_dwordx4 v[0:1], off
	s_mul_i32 s0, s5, 33
	s_cmp_lt_i32 s5, 0
	s_cselect_b32 s5, s0, s1
	s_add_i32 s5, s5, s14
	s_ashr_i32 s0, s5, 31
	s_lshr_b32 s0, s0, 27
	s_add_i32 s0, s5, s0
	s_ashr_i32 s72, s0, 5
	v_bitop3_b32 v14, v17, s9, v14 bitop3:0xde
	s_lshl_b32 s9, s72, 3
	s_sub_i32 s1, 64, s9
	s_min_u32 s14, s1, 8
	s_andn2_b32 s0, s0, 31
	s_sub_i32 s15, s5, s0
	v_cvt_f32_ubyte0_e32 v1, s14
	v_cvt_f32_i32_e32 v0, s15
	v_rcp_iflag_f32_e32 v2, v1
	s_ashr_i32 s0, s15, 30
	s_or_b32 s26, s0, 1
	v_mov_b32_e32 v157, v151
	v_mul_f32_e32 v2, v0, v2
	v_trunc_f32_e32 v2, v2
	v_fma_f32 v0, -v2, v1, v0
	v_cvt_i32_f32_e32 v2, v2
	v_cmp_ge_f32_e64 s[0:1], |v0|, v1
	s_and_b64 s[0:1], s[0:1], exec
	s_cselect_b32 s0, s26, 0
	v_readfirstlane_b32 s1, v2
	s_add_i32 s0, s1, s0
	s_mul_i32 s73, s0, s14
	s_sub_i32 s1, s15, s73
	s_sext_i32_i8 s1, s1
	s_add_i32 s14, s9, s1
	s_ashr_i32 s15, s14, 31
	s_lshl_b64 s[58:59], s[14:15], 19
	s_add_u32 s1, s2, s58
	s_addc_u32 s2, s3, s59
	s_add_u32 s1, s1, 0x400
	s_addc_u32 s15, s2, 0
	s_bfe_i64 s[2:3], s[0:1], 0x80000
	s_lshl_b64 s[2:3], s[2:3], 19
	s_add_u32 s25, s25, s2
	s_addc_u32 s26, s33, s3
	v_lshlrev_b32_e32 v0, 14, v8
	s_add_u32 s25, s25, 0x400
	v_and_b32_e32 v0, 0xffff8000, v0
	s_addc_u32 s33, s26, 0
	v_lshl_add_u32 v0, v9, 11, v0
	v_and_b32_e32 v1, 1, v8
	s_add_u32 s36, s78, s36
	v_lshl_or_b32 v0, v1, 6, v0
	s_addc_u32 s37, s79, s37
	v_lshl_add_u32 v156, v10, 1, v0
	v_lshl_add_u64 v[0:1], s[36:37], 0, v[156:157]
	s_mov_b64 s[58:59], 0xcd88080
	v_lshl_add_u64 v[128:129], v[0:1], 0, s[58:59]
	v_lshlrev_b32_e32 v0, 14, v11
	v_and_b32_e32 v0, 0xffff8000, v0
	s_add_u32 s26, s78, s38
	v_lshl_add_u32 v0, v12, 11, v0
	v_and_b32_e32 v1, 1, v11
	s_addc_u32 s27, s79, s39
	v_lshl_or_b32 v0, v1, 6, v0
	s_add_u32 s74, s26, 0x36c8100
	s_waitcnt vmcnt(6)
	v_lshl_add_u32 v158, v13, 1, v0
	v_mov_b32_e32 v159, v151
	s_addc_u32 s75, s27, 0
	s_add_i32 s62, 0, 0x10000
	s_add_i32 s64, 0, 0x14000
	s_add_i32 s66, 0, 0x18000
	s_add_i32 s68, 0, 0x1c000
	v_lshl_add_u64 v[0:1], s[36:37], 0, v[158:159]
	v_add_u32_e32 v164, s62, v14
	v_add_u32_e32 v166, s64, v14
	s_add_i32 s62, s62, s56
	s_add_i32 s64, s64, s56
	v_add_u32_e32 v167, s66, v14
	v_add_u32_e32 v168, s68, v14
	s_add_i32 s66, s66, s56
	s_add_i32 s68, s68, s56
	v_lshl_add_u64 v[130:131], v[0:1], 0, s[58:59]
	s_mov_b32 s80, -2
	s_mov_b64 s[38:39], 0
	v_add_u32_e32 v165, 0, v15
	s_add_i32 s60, s19, 0xc000
	s_add_i32 s61, s19, 0xe000
	s_add_i32 s63, s62, 0x2000
	s_add_i32 s65, s64, 0x2000
	s_add_i32 s67, s66, 0x2000
	s_add_i32 s69, s68, 0x2000
	v_mov_b32_e32 v0, v151
	v_mov_b32_e32 v1, v151
	v_mov_b32_e32 v2, v151
	v_mov_b32_e32 v3, v151
	v_mov_b32_e32 v4, v151
	v_mov_b32_e32 v5, v151
	v_mov_b32_e32 v6, v151
	v_mov_b32_e32 v7, v151
	v_mov_b32_e32 v12, v151
	v_mov_b32_e32 v13, v151
	v_mov_b32_e32 v14, v151
	v_mov_b32_e32 v15, v151
	v_mov_b32_e32 v20, v151
	v_mov_b32_e32 v21, v151
	v_mov_b32_e32 v22, v151
	v_mov_b32_e32 v23, v151
	v_mov_b32_e32 v28, v151
	v_mov_b32_e32 v29, v151
	v_mov_b32_e32 v30, v151
	v_mov_b32_e32 v31, v151
	v_mov_b32_e32 v36, v151
	v_mov_b32_e32 v37, v151
	v_mov_b32_e32 v38, v151
	v_mov_b32_e32 v39, v151
	v_mov_b32_e32 v44, v151
	v_mov_b32_e32 v45, v151
	v_mov_b32_e32 v46, v151
	v_mov_b32_e32 v47, v151
	v_mov_b32_e32 v52, v151
	v_mov_b32_e32 v53, v151
	v_mov_b32_e32 v54, v151
	v_mov_b32_e32 v55, v151
	v_mov_b32_e32 v8, v151
	v_mov_b32_e32 v9, v151
	v_mov_b32_e32 v10, v151
	v_mov_b32_e32 v11, v151
	v_mov_b32_e32 v16, v151
	v_mov_b32_e32 v17, v151
	v_mov_b32_e32 v18, v151
	v_mov_b32_e32 v19, v151
	v_mov_b32_e32 v24, v151
	v_mov_b32_e32 v25, v151
	v_mov_b32_e32 v26, v151
	v_mov_b32_e32 v27, v151
	v_mov_b32_e32 v32, v151
	v_mov_b32_e32 v33, v151
	v_mov_b32_e32 v34, v151
	v_mov_b32_e32 v35, v151
	v_mov_b32_e32 v40, v151
	v_mov_b32_e32 v41, v151
	v_mov_b32_e32 v42, v151
	v_mov_b32_e32 v43, v151
	v_mov_b32_e32 v48, v151
	v_mov_b32_e32 v49, v151
	v_mov_b32_e32 v50, v151
	v_mov_b32_e32 v51, v151
	v_mov_b32_e32 v56, v151
	v_mov_b32_e32 v57, v151
	v_mov_b32_e32 v58, v151
	v_mov_b32_e32 v59, v151
	v_mov_b32_e32 v60, v151
	v_mov_b32_e32 v61, v151
	v_mov_b32_e32 v62, v151
	v_mov_b32_e32 v63, v151
	v_mov_b32_e32 v64, v151
	v_mov_b32_e32 v65, v151
	v_mov_b32_e32 v66, v151
	v_mov_b32_e32 v67, v151
	v_mov_b32_e32 v68, v151
	v_mov_b32_e32 v69, v151
	v_mov_b32_e32 v70, v151
	v_mov_b32_e32 v71, v151
	v_mov_b32_e32 v72, v151
	v_mov_b32_e32 v73, v151
	v_mov_b32_e32 v74, v151
	v_mov_b32_e32 v75, v151
	v_mov_b32_e32 v80, v151
	v_mov_b32_e32 v81, v151
	v_mov_b32_e32 v82, v151
	v_mov_b32_e32 v83, v151
	v_mov_b32_e32 v88, v151
	v_mov_b32_e32 v89, v151
	v_mov_b32_e32 v90, v151
	v_mov_b32_e32 v91, v151
	v_mov_b32_e32 v96, v151
	v_mov_b32_e32 v97, v151
	v_mov_b32_e32 v98, v151
	v_mov_b32_e32 v99, v151
	v_mov_b32_e32 v104, v151
	v_mov_b32_e32 v105, v151
	v_mov_b32_e32 v106, v151
	v_mov_b32_e32 v107, v151
	v_mov_b32_e32 v108, v151
	v_mov_b32_e32 v109, v151
	v_mov_b32_e32 v110, v151
	v_mov_b32_e32 v111, v151
	v_mov_b32_e32 v76, v151
	v_mov_b32_e32 v77, v151
	v_mov_b32_e32 v78, v151
	v_mov_b32_e32 v79, v151
	v_mov_b32_e32 v84, v151
	v_mov_b32_e32 v85, v151
	v_mov_b32_e32 v86, v151
	v_mov_b32_e32 v87, v151
	v_mov_b32_e32 v92, v151
	v_mov_b32_e32 v93, v151
	v_mov_b32_e32 v94, v151
	v_mov_b32_e32 v95, v151
	v_mov_b32_e32 v100, v151
	v_mov_b32_e32 v101, v151
	v_mov_b32_e32 v102, v151
	v_mov_b32_e32 v103, v151
	v_mov_b32_e32 v112, v151
	v_mov_b32_e32 v113, v151
	v_mov_b32_e32 v114, v151
	v_mov_b32_e32 v115, v151
	v_mov_b32_e32 v116, v151
	v_mov_b32_e32 v117, v151
	v_mov_b32_e32 v118, v151
	v_mov_b32_e32 v119, v151
	v_mov_b32_e32 v120, v151
	v_mov_b32_e32 v121, v151
	v_mov_b32_e32 v122, v151
	v_mov_b32_e32 v123, v151
	v_mov_b32_e32 v124, v151
	v_mov_b32_e32 v125, v151
	v_mov_b32_e32 v126, v151
	v_mov_b32_e32 v127, v151
	s_barrier
	s_getpc_b64 s[98:99]
	v_lshlrev_b32_e32 v246, 7, v202
	v_min_u32_e32 v246, 0x5f80, v246
	v_mov_b32_e32 v247, 0
	v_lshl_add_u64 v[246:247], v[246:247], 0, s[98:99]

.Lus4:
	s_getpc_b64 s[98:99]
	v_lshlrev_b32_e32 v246, 7, v202
	v_min_u32_e32 v246, 0x4f80, v246
	v_mov_b32_e32 v247, 0
	v_lshl_add_u64 v[246:247], v[246:247], 0, s[98:99]

.LBB0_897:
	s_add_u32 s67, s56, 0x100
	s_addc_u32 s68, s57, 0
	s_ashr_i32 s17, s16, 31
	s_lshl_b64 s[36:37], s[16:17], 19
	s_add_u32 s38, s10, s36
	s_addc_u32 s39, s11, s37
	s_and_b64 s[36:37], s[4:5], exec
	s_cselect_b32 s17, s39, s7
	s_cselect_b32 s69, s38, s6
	s_ashr_i32 s15, s14, 31
	s_lshl_b64 s[36:37], s[14:15], 19
	s_add_u32 s36, s20, s36
	s_addc_u32 s37, s21, s37
	s_and_b64 s[58:59], s[4:5], exec
	s_cselect_b32 s15, s37, s57
	s_cselect_b32 s70, s36, s56
	v_lshl_add_u64 v[140:141], s[6:7], 0, v[132:133]
	v_lshl_add_u64 v[142:143], s[6:7], 0, v[134:135]
	s_mov_b32 s71, -2
	s_mov_b64 s[56:57], 0
	s_getpc_b64 s[98:99]
	v_lshlrev_b32_e32 v246, 7, v202
	v_min_u32_e32 v246, 0x2f80, v246
	v_mov_b32_e32 v247, 0
	v_lshl_add_u64 v[246:247], v[246:247], 0, s[98:99]
